# P5 EpiRes: same residual prefetch as P8 (7 of 10 up-front loads issued in the first K-iteration)
# speedup vs baseline: 1.0068x; 1.0068x over previous
.LBB0_882:
	s_xor_b64 s[18:19], s[36:37], -1
	s_and_b64 s[30:31], s[36:37], exec
	s_cselect_b32 s25, s15, s27
	s_cselect_b32 s34, s14, s26
	s_cselect_b32 s36, s17, s29
	s_cselect_b32 s37, s16, s28
	s_add_u32 s26, s26, 0x40080
	s_addc_u32 s27, s27, 0
	s_add_u32 s38, s28, 0x100
	s_addc_u32 s39, s29, 0
	s_mov_b32 s40, -2
	s_waitcnt lgkmcnt(0)
	ds_read_b128 v[128:131], v186
	ds_read_b128 v[132:135], v186 offset:1024
	ds_read_b128 v[136:139], v186 offset:2048
	ds_read_b128 v[140:143], v186 offset:3072
	s_add_u32 s28, s26, 0xfffc0080
	s_addc_u32 s29, s27, -1
	s_cmp_eq_u32 s40, 12
	s_cselect_b32 s31, s25, s29
	s_cselect_b32 s30, s34, s28
	s_cselect_b32 s29, s36, s39
	s_cselect_b32 s28, s37, s38
	v_lshl_add_u64 v[182:183], s[26:27], 0, v[164:165]
	s_add_i32 m0, s45, 0xc000
	ds_read_b128 v[144:147], v187
	ds_read_b128 v[148:151], v187 offset:1024
	ds_read_b128 v[152:155], v187 offset:2048
	ds_read_b128 v[156:159], v187 offset:3072
	ds_read_b128 v[170:173], v187 offset:4096
	ds_read_b128 v[174:177], v187 offset:5120
	ds_read_b128 v[178:181], v187 offset:6144
	ds_read_b128 v[192:195], v187 offset:7168
	global_load_lds_dwordx4 v[182:183], off
	v_lshl_add_u64 v[182:183], s[26:27], 0, v[166:167]
	s_add_i32 m0, s45, 0xe000
	s_nop 0
	global_load_lds_dwordx4 v[182:183], off
	ds_read_b128 v[196:199], v188
	ds_read_b128 v[204:207], v188 offset:1024
	ds_read_b128 v[208:211], v188 offset:2048
	ds_read_b128 v[212:215], v188 offset:3072
	s_waitcnt lgkmcnt(0)
	s_waitcnt vmcnt(8)
	s_barrier
	s_setprio 1
	v_mfma_f32_16x16x32_bf16 v[124:127], v[128:131], v[144:147], 0
	v_mfma_f32_16x16x32_bf16 v[120:123], v[136:139], v[144:147], 0
	v_mfma_f32_16x16x32_bf16 v[108:111], v[128:131], v[152:155], 0
	v_mfma_f32_16x16x32_bf16 v[104:107], v[136:139], v[152:155], 0
	v_mfma_f32_16x16x32_bf16 v[92:95], v[128:131], v[170:173], 0
	v_mfma_f32_16x16x32_bf16 v[88:91], v[136:139], v[170:173], 0
	v_mfma_f32_16x16x32_bf16 v[76:79], v[128:131], v[178:181], 0
	v_mfma_f32_16x16x32_bf16 v[72:75], v[136:139], v[178:181], 0
	v_mfma_f32_16x16x32_bf16 v[124:127], v[132:135], v[148:151], v[124:127]
	v_mfma_f32_16x16x32_bf16 v[120:123], v[140:143], v[148:151], v[120:123]
	v_mfma_f32_16x16x32_bf16 v[108:111], v[132:135], v[156:159], v[108:111]
	v_mfma_f32_16x16x32_bf16 v[104:107], v[140:143], v[156:159], v[104:107]
	v_mfma_f32_16x16x32_bf16 v[92:95], v[132:135], v[174:177], v[92:95]
	v_mfma_f32_16x16x32_bf16 v[88:91], v[140:143], v[174:177], v[88:91]
	v_mfma_f32_16x16x32_bf16 v[76:79], v[132:135], v[192:195], v[76:79]
	v_mfma_f32_16x16x32_bf16 v[72:75], v[140:143], v[192:195], v[72:75]
	v_mfma_f32_16x16x32_bf16 v[116:119], v[196:199], v[144:147], 0
	v_mfma_f32_16x16x32_bf16 v[112:115], v[208:211], v[144:147], 0
	v_mfma_f32_16x16x32_bf16 v[100:103], v[196:199], v[152:155], 0
	v_mfma_f32_16x16x32_bf16 v[96:99], v[208:211], v[152:155], 0
	v_mfma_f32_16x16x32_bf16 v[84:87], v[196:199], v[170:173], 0
	v_mfma_f32_16x16x32_bf16 v[80:83], v[208:211], v[170:173], 0
	v_mfma_f32_16x16x32_bf16 v[68:71], v[196:199], v[178:181], 0
	v_mfma_f32_16x16x32_bf16 v[64:67], v[208:211], v[178:181], 0
	v_mfma_f32_16x16x32_bf16 v[116:119], v[204:207], v[148:151], v[116:119]
	v_mfma_f32_16x16x32_bf16 v[112:115], v[212:215], v[148:151], v[112:115]
	v_mfma_f32_16x16x32_bf16 v[100:103], v[204:207], v[156:159], v[100:103]
	v_mfma_f32_16x16x32_bf16 v[96:99], v[212:215], v[156:159], v[96:99]
	v_mfma_f32_16x16x32_bf16 v[84:87], v[204:207], v[174:177], v[84:87]
	v_mfma_f32_16x16x32_bf16 v[80:83], v[212:215], v[174:177], v[80:83]
	v_mfma_f32_16x16x32_bf16 v[68:71], v[204:207], v[192:195], v[68:71]
	v_mfma_f32_16x16x32_bf16 v[64:67], v[212:215], v[192:195], v[64:67]
	s_setprio 0
	s_barrier
	v_lshl_or_b32 v203, s65, 8, v185
	v_lshlrev_b32_e32 v203, 1, v203
	v_lshl_add_u32 v247, s24, 8, v184
	v_lshl_add_u32 v203, v247, 11, v203
	s_add_u32 s74, s10, 0x8000
	s_addc_u32 s75, s11, 0
	s_add_u32 s76, s10, 0x10000
	s_addc_u32 s77, s11, 0
	s_add_u32 s78, s10, 0x18000
	s_addc_u32 s79, s11, 0
	global_load_dwordx4 v[220:223], v203, s[10:11]
	global_load_dwordx4 v[224:227], v203, s[10:11] offset:64
	global_load_dwordx4 v[228:231], v203, s[74:75]
	global_load_dwordx4 v[232:235], v203, s[74:75] offset:64
	global_load_dwordx4 v[236:239], v203, s[76:77]
	global_load_dwordx4 v[240:243], v203, s[76:77] offset:64
	global_load_dwordx4 v[252:255], v203, s[78:79]
	ds_read_b128 v[144:147], v187 offset:16384
	ds_read_b128 v[148:151], v187 offset:17408
	ds_read_b128 v[152:155], v187 offset:18432
	ds_read_b128 v[156:159], v187 offset:19456
	ds_read_b128 v[170:173], v187 offset:20480
	ds_read_b128 v[174:177], v187 offset:21504
	ds_read_b128 v[178:181], v187 offset:22528
	ds_read_b128 v[192:195], v187 offset:23552
	s_mov_b32 m0, s43
	v_lshl_add_u64 v[182:183], s[28:29], 0, v[160:161]
	global_load_lds_dwordx4 v[182:183], off
	v_lshl_add_u64 v[200:201], s[28:29], 0, v[162:163]
	s_mov_b32 m0, s44
	s_nop 0
	global_load_lds_dwordx4 v[200:201], off
	s_mov_b32 m0, s45
	v_lshl_add_u64 v[216:217], s[30:31], 0, v[160:161]
	global_load_lds_dwordx4 v[216:217], off
	v_lshl_add_u64 v[218:219], s[30:31], 0, v[162:163]
	s_mov_b32 m0, s46
	s_nop 0
	global_load_lds_dwordx4 v[218:219], off
	s_add_u32 s66, s28, 0x40000
	s_addc_u32 s67, s29, 0
	s_mov_b32 m0, s47
	v_lshl_add_u64 v[248:249], s[66:67], 0, v[160:161]
	global_load_lds_dwordx4 v[248:249], off
	v_lshl_add_u64 v[248:249], s[66:67], 0, v[162:163]
	s_mov_b32 m0, s48
	s_nop 0
	global_load_lds_dwordx4 v[248:249], off
	s_waitcnt lgkmcnt(0)
	s_waitcnt vmcnt(15)
	s_barrier
	s_setprio 1
	v_mfma_f32_16x16x32_bf16 v[60:63], v[128:131], v[144:147], 0
	v_mfma_f32_16x16x32_bf16 v[56:59], v[136:139], v[144:147], 0
	v_mfma_f32_16x16x32_bf16 v[44:47], v[128:131], v[152:155], 0
	v_mfma_f32_16x16x32_bf16 v[40:43], v[136:139], v[152:155], 0
	v_mfma_f32_16x16x32_bf16 v[28:31], v[128:131], v[170:173], 0
	v_mfma_f32_16x16x32_bf16 v[24:27], v[136:139], v[170:173], 0
	v_mfma_f32_16x16x32_bf16 v[12:15], v[128:131], v[178:181], 0
	v_mfma_f32_16x16x32_bf16 v[8:11], v[136:139], v[178:181], 0
	v_mfma_f32_16x16x32_bf16 v[60:63], v[132:135], v[148:151], v[60:63]
	v_mfma_f32_16x16x32_bf16 v[56:59], v[140:143], v[148:151], v[56:59]
	v_mfma_f32_16x16x32_bf16 v[44:47], v[132:135], v[156:159], v[44:47]
	v_mfma_f32_16x16x32_bf16 v[40:43], v[140:143], v[156:159], v[40:43]
	v_mfma_f32_16x16x32_bf16 v[28:31], v[132:135], v[174:177], v[28:31]
	v_mfma_f32_16x16x32_bf16 v[24:27], v[140:143], v[174:177], v[24:27]
	v_mfma_f32_16x16x32_bf16 v[12:15], v[132:135], v[192:195], v[12:15]
	v_mfma_f32_16x16x32_bf16 v[8:11], v[140:143], v[192:195], v[8:11]
	v_mfma_f32_16x16x32_bf16 v[52:55], v[196:199], v[144:147], 0
	v_mfma_f32_16x16x32_bf16 v[48:51], v[208:211], v[144:147], 0
	v_mfma_f32_16x16x32_bf16 v[36:39], v[196:199], v[152:155], 0
	v_mfma_f32_16x16x32_bf16 v[32:35], v[208:211], v[152:155], 0
	v_mfma_f32_16x16x32_bf16 v[20:23], v[196:199], v[170:173], 0
	v_mfma_f32_16x16x32_bf16 v[16:19], v[208:211], v[170:173], 0
	v_mfma_f32_16x16x32_bf16 v[4:7], v[196:199], v[178:181], 0
	v_mfma_f32_16x16x32_bf16 v[0:3], v[208:211], v[178:181], 0
	v_mfma_f32_16x16x32_bf16 v[52:55], v[204:207], v[148:151], v[52:55]
	v_mfma_f32_16x16x32_bf16 v[48:51], v[212:215], v[148:151], v[48:51]
	v_mfma_f32_16x16x32_bf16 v[36:39], v[204:207], v[156:159], v[36:39]
	v_mfma_f32_16x16x32_bf16 v[32:35], v[212:215], v[156:159], v[32:35]
	v_mfma_f32_16x16x32_bf16 v[20:23], v[204:207], v[174:177], v[20:23]
	v_mfma_f32_16x16x32_bf16 v[16:19], v[212:215], v[174:177], v[16:19]
	v_mfma_f32_16x16x32_bf16 v[4:7], v[204:207], v[192:195], v[4:7]
	v_mfma_f32_16x16x32_bf16 v[0:3], v[212:215], v[192:195], v[0:3]
	s_setprio 0
	s_barrier
	ds_read_b128 v[128:131], v189
	ds_read_b128 v[132:135], v189 offset:1024
	ds_read_b128 v[136:139], v189 offset:2048
	ds_read_b128 v[140:143], v189 offset:3072
	s_add_u32 s30, s30, 0x40000
	s_addc_u32 s31, s31, 0
	s_mov_b32 m0, s49
	v_lshl_add_u64 v[196:197], s[30:31], 0, v[160:161]
	ds_read_b128 v[144:147], v187 offset:32768
	ds_read_b128 v[148:151], v187 offset:33792
	ds_read_b128 v[152:155], v187 offset:34816
	ds_read_b128 v[156:159], v187 offset:35840
	ds_read_b128 v[170:173], v187 offset:36864
	ds_read_b128 v[174:177], v187 offset:37888
	ds_read_b128 v[178:181], v187 offset:38912
	ds_read_b128 v[192:195], v187 offset:39936
	global_load_lds_dwordx4 v[196:197], off
	v_lshl_add_u64 v[196:197], s[30:31], 0, v[162:163]
	s_mov_b32 m0, s50
	s_nop 0
	global_load_lds_dwordx4 v[196:197], off
	ds_read_b128 v[196:199], v190
	ds_read_b128 v[204:207], v190 offset:1024
	ds_read_b128 v[208:211], v190 offset:2048
	ds_read_b128 v[212:215], v190 offset:3072
	s_waitcnt lgkmcnt(0)
	s_waitcnt vmcnt(15)
	s_barrier
	s_setprio 1
	v_mfma_f32_16x16x32_bf16 v[124:127], v[128:131], v[144:147], v[124:127]
	v_mfma_f32_16x16x32_bf16 v[120:123], v[136:139], v[144:147], v[120:123]
	v_mfma_f32_16x16x32_bf16 v[108:111], v[128:131], v[152:155], v[108:111]
	v_mfma_f32_16x16x32_bf16 v[104:107], v[136:139], v[152:155], v[104:107]
	v_mfma_f32_16x16x32_bf16 v[92:95], v[128:131], v[170:173], v[92:95]
	v_mfma_f32_16x16x32_bf16 v[88:91], v[136:139], v[170:173], v[88:91]
	v_mfma_f32_16x16x32_bf16 v[76:79], v[128:131], v[178:181], v[76:79]
	v_mfma_f32_16x16x32_bf16 v[72:75], v[136:139], v[178:181], v[72:75]
	v_mfma_f32_16x16x32_bf16 v[124:127], v[132:135], v[148:151], v[124:127]
	v_mfma_f32_16x16x32_bf16 v[120:123], v[140:143], v[148:151], v[120:123]
	v_mfma_f32_16x16x32_bf16 v[108:111], v[132:135], v[156:159], v[108:111]
	v_mfma_f32_16x16x32_bf16 v[104:107], v[140:143], v[156:159], v[104:107]
	v_mfma_f32_16x16x32_bf16 v[92:95], v[132:135], v[174:177], v[92:95]
	v_mfma_f32_16x16x32_bf16 v[88:91], v[140:143], v[174:177], v[88:91]
	v_mfma_f32_16x16x32_bf16 v[76:79], v[132:135], v[192:195], v[76:79]
	v_mfma_f32_16x16x32_bf16 v[72:75], v[140:143], v[192:195], v[72:75]
	v_mfma_f32_16x16x32_bf16 v[116:119], v[196:199], v[144:147], v[116:119]
	v_mfma_f32_16x16x32_bf16 v[112:115], v[208:211], v[144:147], v[112:115]
	v_mfma_f32_16x16x32_bf16 v[100:103], v[196:199], v[152:155], v[100:103]
	v_mfma_f32_16x16x32_bf16 v[96:99], v[208:211], v[152:155], v[96:99]
	v_mfma_f32_16x16x32_bf16 v[84:87], v[196:199], v[170:173], v[84:87]
	v_mfma_f32_16x16x32_bf16 v[80:83], v[208:211], v[170:173], v[80:83]
	v_mfma_f32_16x16x32_bf16 v[68:71], v[196:199], v[178:181], v[68:71]
	v_mfma_f32_16x16x32_bf16 v[64:67], v[208:211], v[178:181], v[64:67]
	v_mfma_f32_16x16x32_bf16 v[116:119], v[204:207], v[148:151], v[116:119]
	v_mfma_f32_16x16x32_bf16 v[112:115], v[212:215], v[148:151], v[112:115]
	v_mfma_f32_16x16x32_bf16 v[100:103], v[204:207], v[156:159], v[100:103]
	v_mfma_f32_16x16x32_bf16 v[96:99], v[212:215], v[156:159], v[96:99]
	v_mfma_f32_16x16x32_bf16 v[84:87], v[204:207], v[174:177], v[84:87]
	v_mfma_f32_16x16x32_bf16 v[80:83], v[212:215], v[174:177], v[80:83]
	v_mfma_f32_16x16x32_bf16 v[68:71], v[204:207], v[192:195], v[68:71]
	v_mfma_f32_16x16x32_bf16 v[64:67], v[212:215], v[192:195], v[64:67]
	s_setprio 0
	s_barrier
	ds_read_b128 v[144:147], v187 offset:49152
	ds_read_b128 v[148:151], v187 offset:50176
	ds_read_b128 v[152:155], v187 offset:51200
	ds_read_b128 v[156:159], v187 offset:52224
	ds_read_b128 v[170:173], v187 offset:53248
	ds_read_b128 v[174:177], v187 offset:54272
	ds_read_b128 v[178:181], v187 offset:55296
	ds_read_b128 v[192:195], v187 offset:56320
	s_mov_b32 m0, s54
	v_lshl_add_u64 v[182:183], v[182:183], 0, s[12:13]
	global_load_lds_dwordx4 v[182:183], off
	v_lshl_add_u64 v[182:183], v[200:201], 0, s[12:13]
	s_mov_b32 m0, s55
	s_nop 0
	global_load_lds_dwordx4 v[182:183], off
	s_mov_b32 m0, s56
	v_lshl_add_u64 v[182:183], v[216:217], 0, s[12:13]
	global_load_lds_dwordx4 v[182:183], off
	v_lshl_add_u64 v[182:183], v[218:219], 0, s[12:13]
	s_mov_b32 m0, s57
	s_nop 0
	global_load_lds_dwordx4 v[182:183], off
	s_add_u32 s28, s28, 0x40080
	s_addc_u32 s29, s29, 0
	s_mov_b32 m0, s58
	v_lshl_add_u64 v[248:249], s[28:29], 0, v[160:161]
	global_load_lds_dwordx4 v[248:249], off
	v_lshl_add_u64 v[248:249], s[28:29], 0, v[162:163]
	s_mov_b32 m0, s59
	s_nop 0
	global_load_lds_dwordx4 v[248:249], off
	s_waitcnt lgkmcnt(0)
	s_waitcnt vmcnt(8)
	s_barrier
	s_setprio 1
	v_mfma_f32_16x16x32_bf16 v[60:63], v[128:131], v[144:147], v[60:63]
	v_mfma_f32_16x16x32_bf16 v[56:59], v[136:139], v[144:147], v[56:59]
	v_mfma_f32_16x16x32_bf16 v[44:47], v[128:131], v[152:155], v[44:47]
	v_mfma_f32_16x16x32_bf16 v[40:43], v[136:139], v[152:155], v[40:43]
	v_mfma_f32_16x16x32_bf16 v[28:31], v[128:131], v[170:173], v[28:31]
	v_mfma_f32_16x16x32_bf16 v[24:27], v[136:139], v[170:173], v[24:27]
	v_mfma_f32_16x16x32_bf16 v[12:15], v[128:131], v[178:181], v[12:15]
	v_mfma_f32_16x16x32_bf16 v[8:11], v[136:139], v[178:181], v[8:11]
	v_mfma_f32_16x16x32_bf16 v[60:63], v[132:135], v[148:151], v[60:63]
	v_mfma_f32_16x16x32_bf16 v[56:59], v[140:143], v[148:151], v[56:59]
	v_mfma_f32_16x16x32_bf16 v[44:47], v[132:135], v[156:159], v[44:47]
	v_mfma_f32_16x16x32_bf16 v[40:43], v[140:143], v[156:159], v[40:43]
	v_mfma_f32_16x16x32_bf16 v[28:31], v[132:135], v[174:177], v[28:31]
	v_mfma_f32_16x16x32_bf16 v[24:27], v[140:143], v[174:177], v[24:27]
	v_mfma_f32_16x16x32_bf16 v[12:15], v[132:135], v[192:195], v[12:15]
	v_mfma_f32_16x16x32_bf16 v[8:11], v[140:143], v[192:195], v[8:11]
	v_mfma_f32_16x16x32_bf16 v[52:55], v[196:199], v[144:147], v[52:55]
	v_mfma_f32_16x16x32_bf16 v[48:51], v[208:211], v[144:147], v[48:51]
	v_mfma_f32_16x16x32_bf16 v[36:39], v[196:199], v[152:155], v[36:39]
	v_mfma_f32_16x16x32_bf16 v[32:35], v[208:211], v[152:155], v[32:35]
	v_mfma_f32_16x16x32_bf16 v[20:23], v[196:199], v[170:173], v[20:23]
	v_mfma_f32_16x16x32_bf16 v[16:19], v[208:211], v[170:173], v[16:19]
	v_mfma_f32_16x16x32_bf16 v[4:7], v[196:199], v[178:181], v[4:7]
	v_mfma_f32_16x16x32_bf16 v[0:3], v[208:211], v[178:181], v[0:3]
	v_mfma_f32_16x16x32_bf16 v[52:55], v[204:207], v[148:151], v[52:55]
	v_mfma_f32_16x16x32_bf16 v[48:51], v[212:215], v[148:151], v[48:51]
	v_mfma_f32_16x16x32_bf16 v[36:39], v[204:207], v[156:159], v[36:39]
	v_mfma_f32_16x16x32_bf16 v[32:35], v[212:215], v[156:159], v[32:35]
	v_mfma_f32_16x16x32_bf16 v[20:23], v[204:207], v[174:177], v[20:23]
	v_mfma_f32_16x16x32_bf16 v[16:19], v[212:215], v[174:177], v[16:19]
	v_mfma_f32_16x16x32_bf16 v[4:7], v[204:207], v[192:195], v[4:7]
	v_mfma_f32_16x16x32_bf16 v[0:3], v[212:215], v[192:195], v[0:3]
	s_setprio 0
	s_add_i32 s40, s40, 2
	s_add_u32 s26, s26, 0x100
	s_addc_u32 s27, s27, 0
	s_add_u32 s38, s38, 0x100
	s_addc_u32 s39, s39, 0
	s_cmp_gt_u32 s40, 13
	s_barrier
.LBB0_883:
	ds_read_b128 v[128:131], v186
	ds_read_b128 v[132:135], v186 offset:1024
	ds_read_b128 v[136:139], v186 offset:2048
	ds_read_b128 v[140:143], v186 offset:3072
	s_add_u32 s28, s26, 0xfffc0080
	s_addc_u32 s29, s27, -1
	s_cmp_eq_u32 s40, 12
	s_cselect_b32 s31, s25, s29
	s_cselect_b32 s30, s34, s28
	s_cselect_b32 s29, s36, s39
	s_cselect_b32 s28, s37, s38
	v_lshl_add_u64 v[182:183], s[26:27], 0, v[164:165]
	s_add_i32 m0, s45, 0xc000
	ds_read_b128 v[144:147], v187
	ds_read_b128 v[148:151], v187 offset:1024
	ds_read_b128 v[152:155], v187 offset:2048
	ds_read_b128 v[156:159], v187 offset:3072
	ds_read_b128 v[170:173], v187 offset:4096
	ds_read_b128 v[174:177], v187 offset:5120
	ds_read_b128 v[178:181], v187 offset:6144
	ds_read_b128 v[192:195], v187 offset:7168
	global_load_lds_dwordx4 v[182:183], off
	v_lshl_add_u64 v[182:183], s[26:27], 0, v[166:167]
	s_add_i32 m0, s45, 0xe000
	s_nop 0
	global_load_lds_dwordx4 v[182:183], off
	ds_read_b128 v[196:199], v188
	ds_read_b128 v[204:207], v188 offset:1024
	ds_read_b128 v[208:211], v188 offset:2048
	ds_read_b128 v[212:215], v188 offset:3072
	s_waitcnt lgkmcnt(0)
	s_waitcnt vmcnt(8)
	s_barrier
	s_setprio 1
	v_mfma_f32_16x16x32_bf16 v[124:127], v[128:131], v[144:147], v[124:127]
	v_mfma_f32_16x16x32_bf16 v[120:123], v[136:139], v[144:147], v[120:123]
	v_mfma_f32_16x16x32_bf16 v[108:111], v[128:131], v[152:155], v[108:111]
	v_mfma_f32_16x16x32_bf16 v[104:107], v[136:139], v[152:155], v[104:107]
	v_mfma_f32_16x16x32_bf16 v[92:95], v[128:131], v[170:173], v[92:95]
	v_mfma_f32_16x16x32_bf16 v[88:91], v[136:139], v[170:173], v[88:91]
	v_mfma_f32_16x16x32_bf16 v[76:79], v[128:131], v[178:181], v[76:79]
	v_mfma_f32_16x16x32_bf16 v[72:75], v[136:139], v[178:181], v[72:75]
	v_mfma_f32_16x16x32_bf16 v[124:127], v[132:135], v[148:151], v[124:127]
	v_mfma_f32_16x16x32_bf16 v[120:123], v[140:143], v[148:151], v[120:123]
	v_mfma_f32_16x16x32_bf16 v[108:111], v[132:135], v[156:159], v[108:111]
	v_mfma_f32_16x16x32_bf16 v[104:107], v[140:143], v[156:159], v[104:107]
	v_mfma_f32_16x16x32_bf16 v[92:95], v[132:135], v[174:177], v[92:95]
	v_mfma_f32_16x16x32_bf16 v[88:91], v[140:143], v[174:177], v[88:91]
	v_mfma_f32_16x16x32_bf16 v[76:79], v[132:135], v[192:195], v[76:79]
	v_mfma_f32_16x16x32_bf16 v[72:75], v[140:143], v[192:195], v[72:75]
	v_mfma_f32_16x16x32_bf16 v[116:119], v[196:199], v[144:147], v[116:119]
	v_mfma_f32_16x16x32_bf16 v[112:115], v[208:211], v[144:147], v[112:115]
	v_mfma_f32_16x16x32_bf16 v[100:103], v[196:199], v[152:155], v[100:103]
	v_mfma_f32_16x16x32_bf16 v[96:99], v[208:211], v[152:155], v[96:99]
	v_mfma_f32_16x16x32_bf16 v[84:87], v[196:199], v[170:173], v[84:87]
	v_mfma_f32_16x16x32_bf16 v[80:83], v[208:211], v[170:173], v[80:83]
	v_mfma_f32_16x16x32_bf16 v[68:71], v[196:199], v[178:181], v[68:71]
	v_mfma_f32_16x16x32_bf16 v[64:67], v[208:211], v[178:181], v[64:67]
	v_mfma_f32_16x16x32_bf16 v[116:119], v[204:207], v[148:151], v[116:119]
	v_mfma_f32_16x16x32_bf16 v[112:115], v[212:215], v[148:151], v[112:115]
	v_mfma_f32_16x16x32_bf16 v[100:103], v[204:207], v[156:159], v[100:103]
	v_mfma_f32_16x16x32_bf16 v[96:99], v[212:215], v[156:159], v[96:99]
	v_mfma_f32_16x16x32_bf16 v[84:87], v[204:207], v[174:177], v[84:87]
	v_mfma_f32_16x16x32_bf16 v[80:83], v[212:215], v[174:177], v[80:83]
	v_mfma_f32_16x16x32_bf16 v[68:71], v[204:207], v[192:195], v[68:71]
	v_mfma_f32_16x16x32_bf16 v[64:67], v[212:215], v[192:195], v[64:67]
	s_setprio 0
	s_barrier
	ds_read_b128 v[144:147], v187 offset:16384
	ds_read_b128 v[148:151], v187 offset:17408
	ds_read_b128 v[152:155], v187 offset:18432
	ds_read_b128 v[156:159], v187 offset:19456
	ds_read_b128 v[170:173], v187 offset:20480
	ds_read_b128 v[174:177], v187 offset:21504
	ds_read_b128 v[178:181], v187 offset:22528
	ds_read_b128 v[192:195], v187 offset:23552
	s_mov_b32 m0, s43
	v_lshl_add_u64 v[182:183], s[28:29], 0, v[160:161]
	global_load_lds_dwordx4 v[182:183], off
	v_lshl_add_u64 v[200:201], s[28:29], 0, v[162:163]
	s_mov_b32 m0, s44
	s_nop 0
	global_load_lds_dwordx4 v[200:201], off
	s_mov_b32 m0, s45
	v_lshl_add_u64 v[216:217], s[30:31], 0, v[160:161]
	global_load_lds_dwordx4 v[216:217], off
	v_lshl_add_u64 v[218:219], s[30:31], 0, v[162:163]
	s_mov_b32 m0, s46
	s_nop 0
	global_load_lds_dwordx4 v[218:219], off
	s_add_u32 s66, s28, 0x40000
	s_addc_u32 s67, s29, 0
	s_mov_b32 m0, s47
	v_lshl_add_u64 v[248:249], s[66:67], 0, v[160:161]
	global_load_lds_dwordx4 v[248:249], off
	v_lshl_add_u64 v[248:249], s[66:67], 0, v[162:163]
	s_mov_b32 m0, s48
	s_nop 0
	global_load_lds_dwordx4 v[248:249], off
	s_waitcnt lgkmcnt(0)
	s_waitcnt vmcnt(8)
	s_barrier
	s_setprio 1
	v_mfma_f32_16x16x32_bf16 v[60:63], v[128:131], v[144:147], v[60:63]
	v_mfma_f32_16x16x32_bf16 v[56:59], v[136:139], v[144:147], v[56:59]
	v_mfma_f32_16x16x32_bf16 v[44:47], v[128:131], v[152:155], v[44:47]
	v_mfma_f32_16x16x32_bf16 v[40:43], v[136:139], v[152:155], v[40:43]
	v_mfma_f32_16x16x32_bf16 v[28:31], v[128:131], v[170:173], v[28:31]
	v_mfma_f32_16x16x32_bf16 v[24:27], v[136:139], v[170:173], v[24:27]
	v_mfma_f32_16x16x32_bf16 v[12:15], v[128:131], v[178:181], v[12:15]
	v_mfma_f32_16x16x32_bf16 v[8:11], v[136:139], v[178:181], v[8:11]
	v_mfma_f32_16x16x32_bf16 v[60:63], v[132:135], v[148:151], v[60:63]
	v_mfma_f32_16x16x32_bf16 v[56:59], v[140:143], v[148:151], v[56:59]
	v_mfma_f32_16x16x32_bf16 v[44:47], v[132:135], v[156:159], v[44:47]
	v_mfma_f32_16x16x32_bf16 v[40:43], v[140:143], v[156:159], v[40:43]
	v_mfma_f32_16x16x32_bf16 v[28:31], v[132:135], v[174:177], v[28:31]
	v_mfma_f32_16x16x32_bf16 v[24:27], v[140:143], v[174:177], v[24:27]
	v_mfma_f32_16x16x32_bf16 v[12:15], v[132:135], v[192:195], v[12:15]
	v_mfma_f32_16x16x32_bf16 v[8:11], v[140:143], v[192:195], v[8:11]
	v_mfma_f32_16x16x32_bf16 v[52:55], v[196:199], v[144:147], v[52:55]
	v_mfma_f32_16x16x32_bf16 v[48:51], v[208:211], v[144:147], v[48:51]
	v_mfma_f32_16x16x32_bf16 v[36:39], v[196:199], v[152:155], v[36:39]
	v_mfma_f32_16x16x32_bf16 v[32:35], v[208:211], v[152:155], v[32:35]
	v_mfma_f32_16x16x32_bf16 v[20:23], v[196:199], v[170:173], v[20:23]
	v_mfma_f32_16x16x32_bf16 v[16:19], v[208:211], v[170:173], v[16:19]
	v_mfma_f32_16x16x32_bf16 v[4:7], v[196:199], v[178:181], v[4:7]
	v_mfma_f32_16x16x32_bf16 v[0:3], v[208:211], v[178:181], v[0:3]
	v_mfma_f32_16x16x32_bf16 v[52:55], v[204:207], v[148:151], v[52:55]
	v_mfma_f32_16x16x32_bf16 v[48:51], v[212:215], v[148:151], v[48:51]
	v_mfma_f32_16x16x32_bf16 v[36:39], v[204:207], v[156:159], v[36:39]
	v_mfma_f32_16x16x32_bf16 v[32:35], v[212:215], v[156:159], v[32:35]
	v_mfma_f32_16x16x32_bf16 v[20:23], v[204:207], v[174:177], v[20:23]
	v_mfma_f32_16x16x32_bf16 v[16:19], v[212:215], v[174:177], v[16:19]
	v_mfma_f32_16x16x32_bf16 v[4:7], v[204:207], v[192:195], v[4:7]
	v_mfma_f32_16x16x32_bf16 v[0:3], v[212:215], v[192:195], v[0:3]
	s_setprio 0
	s_barrier
	ds_read_b128 v[128:131], v189
	ds_read_b128 v[132:135], v189 offset:1024
	ds_read_b128 v[136:139], v189 offset:2048
	ds_read_b128 v[140:143], v189 offset:3072
	s_add_u32 s30, s30, 0x40000
	s_addc_u32 s31, s31, 0
	s_mov_b32 m0, s49
	v_lshl_add_u64 v[196:197], s[30:31], 0, v[160:161]
	ds_read_b128 v[144:147], v187 offset:32768
	ds_read_b128 v[148:151], v187 offset:33792
	ds_read_b128 v[152:155], v187 offset:34816
	ds_read_b128 v[156:159], v187 offset:35840
	ds_read_b128 v[170:173], v187 offset:36864
	ds_read_b128 v[174:177], v187 offset:37888
	ds_read_b128 v[178:181], v187 offset:38912
	ds_read_b128 v[192:195], v187 offset:39936
	global_load_lds_dwordx4 v[196:197], off
	v_lshl_add_u64 v[196:197], s[30:31], 0, v[162:163]
	s_mov_b32 m0, s50
	s_nop 0
	global_load_lds_dwordx4 v[196:197], off
	ds_read_b128 v[196:199], v190
	ds_read_b128 v[204:207], v190 offset:1024
	ds_read_b128 v[208:211], v190 offset:2048
	ds_read_b128 v[212:215], v190 offset:3072
	s_waitcnt lgkmcnt(0)
	s_waitcnt vmcnt(8)
	s_barrier
	s_setprio 1
	v_mfma_f32_16x16x32_bf16 v[124:127], v[128:131], v[144:147], v[124:127]
	v_mfma_f32_16x16x32_bf16 v[120:123], v[136:139], v[144:147], v[120:123]
	v_mfma_f32_16x16x32_bf16 v[108:111], v[128:131], v[152:155], v[108:111]
	v_mfma_f32_16x16x32_bf16 v[104:107], v[136:139], v[152:155], v[104:107]
	v_mfma_f32_16x16x32_bf16 v[92:95], v[128:131], v[170:173], v[92:95]
	v_mfma_f32_16x16x32_bf16 v[88:91], v[136:139], v[170:173], v[88:91]
	v_mfma_f32_16x16x32_bf16 v[76:79], v[128:131], v[178:181], v[76:79]
	v_mfma_f32_16x16x32_bf16 v[72:75], v[136:139], v[178:181], v[72:75]
	v_mfma_f32_16x16x32_bf16 v[124:127], v[132:135], v[148:151], v[124:127]
	v_mfma_f32_16x16x32_bf16 v[120:123], v[140:143], v[148:151], v[120:123]
	v_mfma_f32_16x16x32_bf16 v[108:111], v[132:135], v[156:159], v[108:111]
	v_mfma_f32_16x16x32_bf16 v[104:107], v[140:143], v[156:159], v[104:107]
	v_mfma_f32_16x16x32_bf16 v[92:95], v[132:135], v[174:177], v[92:95]
	v_mfma_f32_16x16x32_bf16 v[88:91], v[140:143], v[174:177], v[88:91]
	v_mfma_f32_16x16x32_bf16 v[76:79], v[132:135], v[192:195], v[76:79]
	v_mfma_f32_16x16x32_bf16 v[72:75], v[140:143], v[192:195], v[72:75]
	v_mfma_f32_16x16x32_bf16 v[116:119], v[196:199], v[144:147], v[116:119]
	v_mfma_f32_16x16x32_bf16 v[112:115], v[208:211], v[144:147], v[112:115]
	v_mfma_f32_16x16x32_bf16 v[100:103], v[196:199], v[152:155], v[100:103]
	v_mfma_f32_16x16x32_bf16 v[96:99], v[208:211], v[152:155], v[96:99]
	v_mfma_f32_16x16x32_bf16 v[84:87], v[196:199], v[170:173], v[84:87]
	v_mfma_f32_16x16x32_bf16 v[80:83], v[208:211], v[170:173], v[80:83]
	v_mfma_f32_16x16x32_bf16 v[68:71], v[196:199], v[178:181], v[68:71]
	v_mfma_f32_16x16x32_bf16 v[64:67], v[208:211], v[178:181], v[64:67]
	v_mfma_f32_16x16x32_bf16 v[116:119], v[204:207], v[148:151], v[116:119]
	v_mfma_f32_16x16x32_bf16 v[112:115], v[212:215], v[148:151], v[112:115]
	v_mfma_f32_16x16x32_bf16 v[100:103], v[204:207], v[156:159], v[100:103]
	v_mfma_f32_16x16x32_bf16 v[96:99], v[212:215], v[156:159], v[96:99]
	v_mfma_f32_16x16x32_bf16 v[84:87], v[204:207], v[174:177], v[84:87]
	v_mfma_f32_16x16x32_bf16 v[80:83], v[212:215], v[174:177], v[80:83]
	v_mfma_f32_16x16x32_bf16 v[68:71], v[204:207], v[192:195], v[68:71]
	v_mfma_f32_16x16x32_bf16 v[64:67], v[212:215], v[192:195], v[64:67]
	s_setprio 0
	s_barrier
	ds_read_b128 v[144:147], v187 offset:49152
	ds_read_b128 v[148:151], v187 offset:50176
	ds_read_b128 v[152:155], v187 offset:51200
	ds_read_b128 v[156:159], v187 offset:52224
	ds_read_b128 v[170:173], v187 offset:53248
	ds_read_b128 v[174:177], v187 offset:54272
	ds_read_b128 v[178:181], v187 offset:55296
	ds_read_b128 v[192:195], v187 offset:56320
	s_mov_b32 m0, s54
	v_lshl_add_u64 v[182:183], v[182:183], 0, s[12:13]
	global_load_lds_dwordx4 v[182:183], off
	v_lshl_add_u64 v[182:183], v[200:201], 0, s[12:13]
	s_mov_b32 m0, s55
	s_nop 0
	global_load_lds_dwordx4 v[182:183], off
	s_mov_b32 m0, s56
	v_lshl_add_u64 v[182:183], v[216:217], 0, s[12:13]
	global_load_lds_dwordx4 v[182:183], off
	v_lshl_add_u64 v[182:183], v[218:219], 0, s[12:13]
	s_mov_b32 m0, s57
	s_nop 0
	global_load_lds_dwordx4 v[182:183], off
	s_add_u32 s28, s28, 0x40080
	s_addc_u32 s29, s29, 0
	s_mov_b32 m0, s58
	v_lshl_add_u64 v[248:249], s[28:29], 0, v[160:161]
	global_load_lds_dwordx4 v[248:249], off
	v_lshl_add_u64 v[248:249], s[28:29], 0, v[162:163]
	s_mov_b32 m0, s59
	s_nop 0
	global_load_lds_dwordx4 v[248:249], off
	s_waitcnt lgkmcnt(0)
	s_waitcnt vmcnt(8)
	s_barrier
	s_setprio 1
	v_mfma_f32_16x16x32_bf16 v[60:63], v[128:131], v[144:147], v[60:63]
	v_mfma_f32_16x16x32_bf16 v[56:59], v[136:139], v[144:147], v[56:59]
	v_mfma_f32_16x16x32_bf16 v[44:47], v[128:131], v[152:155], v[44:47]
	v_mfma_f32_16x16x32_bf16 v[40:43], v[136:139], v[152:155], v[40:43]
	v_mfma_f32_16x16x32_bf16 v[28:31], v[128:131], v[170:173], v[28:31]
	v_mfma_f32_16x16x32_bf16 v[24:27], v[136:139], v[170:173], v[24:27]
	v_mfma_f32_16x16x32_bf16 v[12:15], v[128:131], v[178:181], v[12:15]
	v_mfma_f32_16x16x32_bf16 v[8:11], v[136:139], v[178:181], v[8:11]
	v_mfma_f32_16x16x32_bf16 v[60:63], v[132:135], v[148:151], v[60:63]
	v_mfma_f32_16x16x32_bf16 v[56:59], v[140:143], v[148:151], v[56:59]
	v_mfma_f32_16x16x32_bf16 v[44:47], v[132:135], v[156:159], v[44:47]
	v_mfma_f32_16x16x32_bf16 v[40:43], v[140:143], v[156:159], v[40:43]
	v_mfma_f32_16x16x32_bf16 v[28:31], v[132:135], v[174:177], v[28:31]
	v_mfma_f32_16x16x32_bf16 v[24:27], v[140:143], v[174:177], v[24:27]
	v_mfma_f32_16x16x32_bf16 v[12:15], v[132:135], v[192:195], v[12:15]
	v_mfma_f32_16x16x32_bf16 v[8:11], v[140:143], v[192:195], v[8:11]
	v_mfma_f32_16x16x32_bf16 v[52:55], v[196:199], v[144:147], v[52:55]
	v_mfma_f32_16x16x32_bf16 v[48:51], v[208:211], v[144:147], v[48:51]
	v_mfma_f32_16x16x32_bf16 v[36:39], v[196:199], v[152:155], v[36:39]
	v_mfma_f32_16x16x32_bf16 v[32:35], v[208:211], v[152:155], v[32:35]
	v_mfma_f32_16x16x32_bf16 v[20:23], v[196:199], v[170:173], v[20:23]
	v_mfma_f32_16x16x32_bf16 v[16:19], v[208:211], v[170:173], v[16:19]
	v_mfma_f32_16x16x32_bf16 v[4:7], v[196:199], v[178:181], v[4:7]
	v_mfma_f32_16x16x32_bf16 v[0:3], v[208:211], v[178:181], v[0:3]
	v_mfma_f32_16x16x32_bf16 v[52:55], v[204:207], v[148:151], v[52:55]
	v_mfma_f32_16x16x32_bf16 v[48:51], v[212:215], v[148:151], v[48:51]
	v_mfma_f32_16x16x32_bf16 v[36:39], v[204:207], v[156:159], v[36:39]
	v_mfma_f32_16x16x32_bf16 v[32:35], v[212:215], v[156:159], v[32:35]
	v_mfma_f32_16x16x32_bf16 v[20:23], v[204:207], v[174:177], v[20:23]
	v_mfma_f32_16x16x32_bf16 v[16:19], v[212:215], v[174:177], v[16:19]
	v_mfma_f32_16x16x32_bf16 v[4:7], v[204:207], v[192:195], v[4:7]
	v_mfma_f32_16x16x32_bf16 v[0:3], v[212:215], v[192:195], v[0:3]
	s_setprio 0
	s_add_i32 s40, s40, 2
	s_add_u32 s26, s26, 0x100
	s_addc_u32 s27, s27, 0
	s_add_u32 s38, s38, 0x100
	s_addc_u32 s39, s39, 0
	s_cmp_gt_u32 s40, 13
	s_barrier
	s_cbranch_scc0 .LBB0_883
	v_lshl_or_b32 v128, s65, 8, v185
	v_lshl_add_u32 v170, s24, 8, v184
	v_ashrrev_i32_e32 v129, 31, v128
	v_lshlrev_b64 v[174:175], 1, v[128:129]
	v_ashrrev_i32_e32 v171, 31, v170
	v_lshl_add_u64 v[128:129], s[10:11], 0, v[174:175]
	v_lshlrev_b64 v[204:205], 11, v[170:171]
	v_lshl_add_u64 v[130:131], v[128:129], 0, v[204:205]
	v_mov_b32_e32 v194, v220
	v_mov_b32_e32 v195, v221
	v_mov_b32_e32 v196, v222
	v_mov_b32_e32 v197, v223
	v_mov_b32_e32 v198, v224
	v_mov_b32_e32 v199, v225
	v_mov_b32_e32 v200, v226
	v_mov_b32_e32 v201, v227
	v_or_b32_e32 v130, 16, v170
	v_or_b32_e32 v132, 32, v170
	v_or_b32_e32 v134, 48, v170
	v_ashrrev_i32_e32 v131, 31, v130
	v_ashrrev_i32_e32 v133, 31, v132
	v_ashrrev_i32_e32 v135, 31, v134
	v_lshlrev_b64 v[182:183], 11, v[130:131]
	v_add_u32_e32 v178, 0x80, v170
	v_lshlrev_b64 v[180:181], 11, v[132:133]
	v_lshlrev_b64 v[176:177], 11, v[134:135]
	v_lshl_add_u64 v[132:133], v[128:129], 0, v[182:183]
	v_ashrrev_i32_e32 v179, 31, v178
	v_lshl_add_u64 v[134:135], v[128:129], 0, v[180:181]
	v_lshl_add_u64 v[128:129], v[128:129], 0, v[176:177]
	v_mov_b32_e32 v156, v228
	v_mov_b32_e32 v157, v229
	v_mov_b32_e32 v158, v230
	v_mov_b32_e32 v159, v231
	v_mov_b32_e32 v152, v232
	v_mov_b32_e32 v153, v233
	v_mov_b32_e32 v154, v234
	v_mov_b32_e32 v155, v235
	v_mov_b32_e32 v148, v236
	v_mov_b32_e32 v149, v237
	v_mov_b32_e32 v150, v238
	v_mov_b32_e32 v151, v239
	v_mov_b32_e32 v144, v240
	v_mov_b32_e32 v145, v241
	v_mov_b32_e32 v146, v242
	v_mov_b32_e32 v147, v243
	v_mov_b32_e32 v140, v252
	v_mov_b32_e32 v141, v253
	v_mov_b32_e32 v142, v254
	v_mov_b32_e32 v143, v255
	global_load_dwordx4 v[136:139], v[128:129], off offset:64
	v_lshlrev_b64 v[130:131], 11, v[178:179]
	v_lshl_add_u64 v[130:131], s[10:11], 0, v[130:131]
	v_lshl_add_u64 v[172:173], v[130:131], 0, v[174:175]
	global_load_dwordx4 v[132:135], v[172:173], off
	global_load_dwordx4 v[128:131], v[172:173], off offset:64
	v_and_b32_e32 v192, 64, v191
	v_xor_b32_e32 v179, 16, v191
	v_add_u32_e32 v192, 64, v192
	v_xor_b32_e32 v193, 32, v191
	v_cmp_lt_i32_e32 vcc, v179, v192
	v_lshl_add_u64 v[204:205], s[10:11], 0, v[204:205]
	v_lshl_add_u64 v[204:205], v[204:205], 0, v[174:175]
	v_cndmask_b32_e32 v179, v191, v179, vcc
	v_cmp_lt_i32_e32 vcc, v193, v192
	v_lshlrev_b32_e32 v192, 2, v179
	s_lshl_b32 s24, s65, 2
	v_cndmask_b32_e32 v193, v191, v193, vcc
	v_lshlrev_b32_e32 v179, 2, v193
	s_or_b32 s27, s24, s53
	s_mul_hi_i32 s26, s27, 0x21000
	s_mul_i32 s27, s27, 0x21000
	v_lshlrev_b32_e32 v206, 16, v194
	v_and_b32_e32 v207, 0xffff0000, v194
	v_lshlrev_b32_e32 v194, 16, v195
	v_and_b32_e32 v195, 0xffff0000, v195
	v_lshlrev_b32_e32 v208, 16, v196
	v_and_b32_e32 v209, 0xffff0000, v196
	v_lshlrev_b32_e32 v196, 16, v197
	v_and_b32_e32 v197, 0xffff0000, v197
	v_lshlrev_b32_e32 v212, 16, v200
	v_and_b32_e32 v213, 0xffff0000, v200
	v_lshlrev_b32_e32 v200, 16, v201
	v_and_b32_e32 v201, 0xffff0000, v201
	v_pk_add_f32 v[126:127], v[126:127], v[194:195]
	v_pk_add_f32 v[124:125], v[124:125], v[206:207]
	v_pk_add_f32 v[122:123], v[122:123], v[196:197]
	v_pk_add_f32 v[120:121], v[120:121], v[208:209]
	v_lshlrev_b32_e32 v210, 16, v198
	v_and_b32_e32 v211, 0xffff0000, v198
	v_lshlrev_b32_e32 v198, 16, v199
	v_and_b32_e32 v199, 0xffff0000, v199
	v_pk_add_f32 v[194:195], v[114:115], v[200:201]
	v_pk_add_f32 v[196:197], v[112:113], v[212:213]
	v_cvt_pk_bf16_f32 v112, v124, v125
	v_cvt_pk_bf16_f32 v113, v126, v127
	v_mul_f32_e32 v114, v125, v125
	v_mul_f32_e32 v115, v127, v127
	v_mul_f32_e32 v125, v121, v121
	v_mul_f32_e32 v127, v123, v123
	v_pk_add_f32 v[118:119], v[118:119], v[198:199]
	v_pk_add_f32 v[116:117], v[116:117], v[210:211]
	v_fmac_f32_e32 v114, v124, v124
	v_fmac_f32_e32 v115, v126, v126
	v_fmac_f32_e32 v125, v120, v120
	v_fmac_f32_e32 v127, v122, v122
	v_mul_f32_e32 v193, v117, v117
	v_mul_f32_e32 v198, v119, v119
	v_add_f32_e32 v114, v114, v115
	v_add_f32_e32 v115, v125, v127
	v_mul_f32_e32 v124, v197, v197
	v_mul_f32_e32 v125, v195, v195
	v_fmac_f32_e32 v193, v116, v116
	v_fmac_f32_e32 v198, v118, v118
	v_fmac_f32_e32 v124, v196, v196
	v_fmac_f32_e32 v125, v194, v194
	v_add_f32_e32 v114, v114, v115
	v_add_f32_e32 v115, v193, v198
	v_add_f32_e32 v124, v124, v125
	v_add_f32_e32 v115, v115, v124
	v_add_f32_e32 v124, v114, v115
	ds_bpermute_b32 v125, v192, v124
	v_cvt_pk_bf16_f32 v114, v120, v121
	v_cvt_pk_bf16_f32 v115, v122, v123
	global_store_dwordx4 v[204:205], v[112:115], off
	s_waitcnt lgkmcnt(0)
	s_nop 0
	v_add_f32_e32 v112, v124, v125
	ds_bpermute_b32 v113, v179, v112
	v_cvt_pk_bf16_f32 v114, v116, v117
	v_cvt_pk_bf16_f32 v115, v118, v119
	v_cvt_pk_bf16_f32 v116, v196, v197
	v_cvt_pk_bf16_f32 v117, v194, v195
	global_store_dwordx4 v[204:205], v[114:117], off offset:64
	s_and_saveexec_b64 s[24:25], s[4:5]
	s_cbranch_execz .LBB0_886
	s_add_u32 s28, s51, s27
	s_addc_u32 s29, s52, s26
	s_waitcnt lgkmcnt(0)
	v_add_f32_e32 v114, v112, v113
	v_lshl_add_u64 v[112:113], v[170:171], 2, s[28:29]
	global_store_dword v[112:113], v114, off

.LBB0_890:
	s_or_b64 exec, exec, s[24:25]
	v_or_b32_e32 v80, 48, v178
	s_waitcnt lgkmcnt(0)
	v_ashrrev_i32_e32 v81, 31, v80
	v_lshlrev_b64 v[80:81], 11, v[80:81]
	v_lshl_add_u64 v[80:81], s[10:11], 0, v[80:81]
	v_lshl_add_u64 v[88:89], v[80:81], 0, v[174:175]
	global_load_dwordx4 v[84:87], v[88:89], off
	global_load_dwordx4 v[80:83], v[88:89], off offset:64
	v_lshlrev_b32_e32 v92, 16, v141
	v_and_b32_e32 v93, 0xffff0000, v141
	v_lshlrev_b32_e32 v90, 16, v140
	v_and_b32_e32 v91, 0xffff0000, v140
	v_pk_add_f32 v[78:79], v[78:79], v[92:93]
	v_lshlrev_b32_e32 v92, 16, v143
	v_and_b32_e32 v93, 0xffff0000, v143
	v_pk_add_f32 v[76:77], v[76:77], v[90:91]
	v_lshlrev_b32_e32 v90, 16, v142
	v_and_b32_e32 v91, 0xffff0000, v142
	v_pk_add_f32 v[74:75], v[74:75], v[92:93]
	s_waitcnt vmcnt(16)
	v_lshlrev_b32_e32 v92, 16, v137
	v_and_b32_e32 v93, 0xffff0000, v137
	v_pk_add_f32 v[72:73], v[72:73], v[90:91]
	v_lshlrev_b32_e32 v90, 16, v136
	v_and_b32_e32 v91, 0xffff0000, v136
	v_pk_add_f32 v[70:71], v[70:71], v[92:93]
	v_lshlrev_b32_e32 v92, 16, v139
	v_and_b32_e32 v93, 0xffff0000, v139
	v_pk_add_f32 v[68:69], v[68:69], v[90:91]
	v_lshlrev_b32_e32 v90, 16, v138
	v_and_b32_e32 v91, 0xffff0000, v138
	v_pk_add_f32 v[92:93], v[66:67], v[92:93]
	v_mul_f32_e32 v66, v77, v77
	v_mul_f32_e32 v67, v79, v79
	v_pk_add_f32 v[90:91], v[64:65], v[90:91]
	v_lshl_add_u64 v[64:65], s[10:11], 0, v[176:177]
	v_fmac_f32_e32 v66, v76, v76
	v_fmac_f32_e32 v67, v78, v78
	v_lshl_add_u64 v[94:95], v[64:65], 0, v[174:175]
	v_cvt_pk_bf16_f32 v64, v76, v77
	v_add_f32_e32 v66, v66, v67
	v_mul_f32_e32 v67, v73, v73
	v_mul_f32_e32 v76, v75, v75
	v_fmac_f32_e32 v67, v72, v72
	v_fmac_f32_e32 v76, v74, v74
	v_add_f32_e32 v67, v67, v76
	v_add_f32_e32 v66, v66, v67
	v_mul_f32_e32 v67, v69, v69
	v_mul_f32_e32 v76, v71, v71
	v_fmac_f32_e32 v67, v68, v68
	v_fmac_f32_e32 v76, v70, v70
	v_add_f32_e32 v67, v67, v76
	v_mul_f32_e32 v76, v91, v91
	v_mul_f32_e32 v77, v93, v93
	v_fmac_f32_e32 v76, v90, v90
	v_fmac_f32_e32 v77, v92, v92
	v_add_f32_e32 v76, v76, v77
	v_add_f32_e32 v67, v67, v76
	v_add_f32_e32 v76, v66, v67
	ds_bpermute_b32 v77, v192, v76
	v_cvt_pk_bf16_f32 v65, v78, v79
	v_cvt_pk_bf16_f32 v66, v72, v73
	v_cvt_pk_bf16_f32 v67, v74, v75
	global_store_dwordx4 v[94:95], v[64:67], off
	s_waitcnt lgkmcnt(0)
	s_nop 0
	v_add_f32_e32 v64, v76, v77
	ds_bpermute_b32 v65, v179, v64
	v_cvt_pk_bf16_f32 v66, v68, v69
	v_cvt_pk_bf16_f32 v67, v70, v71
	v_cvt_pk_bf16_f32 v68, v90, v91
	v_cvt_pk_bf16_f32 v69, v92, v93
	global_store_dwordx4 v[94:95], v[66:69], off offset:64
	s_and_saveexec_b64 s[24:25], s[4:5]
	s_cbranch_execz .LBB0_892
	s_add_u32 s28, s51, s27
	s_addc_u32 s29, s52, s26
	s_waitcnt lgkmcnt(0)
	v_add_f32_e32 v66, v64, v65
	v_lshl_add_u64 v[64:65], v[170:171], 2, s[28:29]
	global_store_dword v[64:65], v66, off offset:192
.LBB0_892:
	s_or_b64 exec, exec, s[24:25]
	s_waitcnt vmcnt(17)
	v_lshlrev_b32_e32 v66, 16, v133
	v_and_b32_e32 v67, 0xffff0000, v133
	v_pk_add_f32 v[62:63], v[62:63], v[66:67]
	v_lshlrev_b32_e32 v66, 16, v135
	v_and_b32_e32 v67, 0xffff0000, v135
	v_lshlrev_b32_e32 v64, 16, v132
	s_waitcnt lgkmcnt(0)
	v_and_b32_e32 v65, 0xffff0000, v132
	v_pk_add_f32 v[58:59], v[58:59], v[66:67]
	v_lshlrev_b32_e32 v66, 16, v129
	v_and_b32_e32 v67, 0xffff0000, v129
	v_pk_add_f32 v[60:61], v[60:61], v[64:65]
	v_lshlrev_b32_e32 v64, 16, v134
	v_and_b32_e32 v65, 0xffff0000, v134
	v_pk_add_f32 v[54:55], v[54:55], v[66:67]
	v_lshlrev_b32_e32 v66, 16, v131
	v_and_b32_e32 v67, 0xffff0000, v131
	v_pk_add_f32 v[56:57], v[56:57], v[64:65]
	v_lshlrev_b32_e32 v64, 16, v128
	v_and_b32_e32 v65, 0xffff0000, v128
	v_pk_add_f32 v[66:67], v[50:51], v[66:67]
	v_mul_f32_e32 v50, v61, v61
	v_mul_f32_e32 v51, v63, v63
	v_pk_add_f32 v[52:53], v[52:53], v[64:65]
	v_lshlrev_b32_e32 v64, 16, v130
	v_and_b32_e32 v65, 0xffff0000, v130
	v_fmac_f32_e32 v50, v60, v60
	v_fmac_f32_e32 v51, v62, v62
	v_pk_add_f32 v[64:65], v[48:49], v[64:65]
	v_cvt_pk_bf16_f32 v48, v60, v61
	v_add_f32_e32 v50, v50, v51
	v_mul_f32_e32 v51, v57, v57
	v_mul_f32_e32 v60, v59, v59
	v_fmac_f32_e32 v51, v56, v56
	v_fmac_f32_e32 v60, v58, v58
	v_add_f32_e32 v51, v51, v60
	v_add_f32_e32 v50, v50, v51
	v_mul_f32_e32 v51, v53, v53
	v_mul_f32_e32 v60, v55, v55
	v_fmac_f32_e32 v51, v52, v52
	v_fmac_f32_e32 v60, v54, v54
	v_add_f32_e32 v51, v51, v60
	v_mul_f32_e32 v60, v65, v65
	v_mul_f32_e32 v61, v67, v67
	v_fmac_f32_e32 v60, v64, v64
	v_fmac_f32_e32 v61, v66, v66
	v_add_f32_e32 v60, v60, v61
	v_add_f32_e32 v51, v51, v60
	v_add_f32_e32 v60, v50, v51
	ds_bpermute_b32 v61, v192, v60
	v_cvt_pk_bf16_f32 v49, v62, v63
	v_cvt_pk_bf16_f32 v50, v56, v57
	v_cvt_pk_bf16_f32 v51, v58, v59
	global_store_dwordx4 v[172:173], v[48:51], off
	s_waitcnt lgkmcnt(0)
	s_nop 0
	v_add_f32_e32 v48, v60, v61
	ds_bpermute_b32 v49, v179, v48
	v_cvt_pk_bf16_f32 v50, v52, v53
	v_cvt_pk_bf16_f32 v51, v54, v55
	v_cvt_pk_bf16_f32 v52, v64, v65
	v_cvt_pk_bf16_f32 v53, v66, v67
	global_store_dwordx4 v[172:173], v[50:53], off offset:64
	s_and_saveexec_b64 s[24:25], s[4:5]
	s_cbranch_execz .LBB0_894
	s_add_u32 s28, s51, s27
	s_addc_u32 s29, s52, s26
	s_waitcnt lgkmcnt(0)
	v_add_f32_e32 v50, v48, v49
	v_lshl_add_u64 v[48:49], v[170:171], 2, s[28:29]
	global_store_dword v[48:49], v50, off offset:512
